# LN1 stores per-row mean/rstd instead of the normalised f32 rows; FFN-out epilogue rebuilds the residual from the out-proj result in place (same f32 ops)
# speedup vs baseline: 1.0055x; 1.0055x over previous
.LBB0_53:
	s_mul_i32 s10, s9, 0x5000
	v_add_u32_e32 v156, s10, v142
	v_lshl_add_u64 v[126:127], v[124:125], 0, s[0:1]
	v_readfirstlane_b32 s10, v156
	v_add_u32_e32 v136, 0x1000, v156
	v_lshl_add_u64 v[134:135], v[126:127], 0, s[2:3]
	s_mov_b32 m0, s10
	v_lshl_add_u64 v[138:139], v[122:123], 0, s[0:1]
	v_readfirstlane_b32 s10, v136
	s_waitcnt vmcnt(5)
	s_barrier
	global_load_lds_dwordx4 v[134:135], off
	v_lshl_add_u64 v[134:135], v[138:139], 0, s[2:3]
	s_mov_b32 m0, s10
	v_add_u32_e32 v140, 0x2000, v156
	global_load_lds_dwordx4 v[134:135], off
	v_lshl_add_u64 v[134:135], v[120:121], 0, s[0:1]
	v_readfirstlane_b32 s10, v140
	v_lshl_add_u64 v[136:137], v[134:135], 0, s[2:3]
	s_mov_b32 m0, s10
	v_add_u32_e32 v154, 0x3000, v156
	global_load_lds_dwordx4 v[136:137], off
	v_lshl_add_u64 v[136:137], v[118:119], 0, s[0:1]
	v_readfirstlane_b32 s10, v154
	v_lshl_add_u64 v[140:141], v[136:137], 0, s[2:3]
	s_mov_b32 m0, s10
	v_add_u32_e32 v156, 0x4000, v156
	global_load_lds_dwordx4 v[140:141], off
	v_lshl_add_u64 v[140:141], v[116:117], 0, s[0:1]
	v_readfirstlane_b32 s10, v156
	v_lshl_add_u64 v[154:155], v[140:141], 0, s[2:3]
	s_mov_b32 m0, s10
	s_mul_i32 s10, s8, 0x5000
	global_load_lds_dwordx4 v[154:155], off
	v_or_b32_e32 v154, s10, v147
	v_add_u32_e32 v170, v154, v128
	ds_read_b128 v[154:157], v170
	ds_read_b128 v[158:161], v170 offset:1024
	ds_read_b128 v[162:165], v170 offset:2048
	ds_read_b128 v[166:169], v170 offset:3072
	ds_read_b128 v[200:203], v170 offset:4096
	ds_read_b128 v[204:207], v170 offset:5120
	v_or_b32_e32 v170, s10, v149
	v_add_u32_e32 v170, v170, v148
	s_add_i32 s8, s8, 1
	s_add_i32 s9, s9, 1
	ds_read_b128 v[208:211], v170 offset:12288
	ds_read_b128 v[212:215], v170 offset:13312
	ds_read_b128 v[216:219], v170 offset:14336
	ds_read_b128 v[220:223], v170 offset:15360
	s_cmp_lg_u32 s8, 3
	s_cselect_b32 s8, s8, 0
	s_cmp_lg_u32 s9, 3
	s_cselect_b32 s9, s9, 0
	s_mul_i32 s10, s9, 0x5000
	s_waitcnt lgkmcnt(0)
	v_mfma_f32_16x16x32_bf16 v[92:95], v[208:211], v[154:157], v[92:95]
	v_lshl_add_u64 v[126:127], v[126:127], 0, s[30:31]
	s_waitcnt vmcnt(5)
	s_barrier
	v_mfma_f32_16x16x32_bf16 v[88:91], v[212:215], v[154:157], v[88:91]
	s_add_i32 s9, s9, 1
	v_mfma_f32_16x16x32_bf16 v[84:87], v[216:219], v[154:157], v[84:87]
	v_mfma_f32_16x16x32_bf16 v[80:83], v[220:223], v[154:157], v[80:83]
	v_add_u32_e32 v154, s10, v142
	s_nop 0
	v_readfirstlane_b32 s10, v154
	s_mov_b32 m0, s10
	v_mfma_f32_16x16x32_bf16 v[76:79], v[208:211], v[158:161], v[76:79]
	global_load_lds_dwordx4 v[126:127], off
	v_lshl_add_u64 v[126:127], v[138:139], 0, s[30:31]
	v_add_u32_e32 v138, 0x1000, v154
	v_mfma_f32_16x16x32_bf16 v[72:75], v[212:215], v[158:161], v[72:75]
	v_readfirstlane_b32 s10, v138
	s_mov_b32 m0, s10
	s_nop 0
	global_load_lds_dwordx4 v[126:127], off
	v_lshl_add_u64 v[126:127], v[134:135], 0, s[30:31]
	v_add_u32_e32 v134, 0x2000, v154
	v_mfma_f32_16x16x32_bf16 v[68:71], v[216:219], v[158:161], v[68:71]
	v_readfirstlane_b32 s10, v134
	v_add_u32_e32 v134, 0x3000, v154
	s_mov_b32 m0, s10
	v_readfirstlane_b32 s10, v134
	v_add_u32_e32 v134, 0x4000, v154
	global_load_lds_dwordx4 v[126:127], off
	v_lshl_add_u64 v[126:127], v[136:137], 0, s[30:31]
	s_mov_b32 m0, s10
	v_readfirstlane_b32 s10, v134
	global_load_lds_dwordx4 v[126:127], off
	v_lshl_add_u64 v[126:127], v[140:141], 0, s[30:31]
	s_mov_b32 m0, s10
	s_mul_i32 s10, s8, 0x5000
	global_load_lds_dwordx4 v[126:127], off
	v_or_b32_e32 v126, s10, v147
	v_add_u32_e32 v126, v126, v128
	v_mfma_f32_16x16x32_bf16 v[64:67], v[220:223], v[158:161], v[64:67]
	s_add_i32 s8, s8, 1
	s_cmp_lg_u32 s8, 3
	s_cselect_b32 s8, s8, 0
	v_mfma_f32_16x16x32_bf16 v[60:63], v[208:211], v[162:165], v[60:63]
	s_cmp_lg_u32 s9, 3
	s_cselect_b32 s9, s9, 0
	s_add_u32 s0, s0, 0x80
	v_mfma_f32_16x16x32_bf16 v[56:59], v[212:215], v[162:165], v[56:59]
	s_addc_u32 s1, s1, 0
	s_cmpk_eq_i32 s0, 0x1580
	v_mfma_f32_16x16x32_bf16 v[52:55], v[216:219], v[162:165], v[52:55]
	v_mfma_f32_16x16x32_bf16 v[48:51], v[220:223], v[162:165], v[48:51]
	v_mfma_f32_16x16x32_bf16 v[44:47], v[208:211], v[166:169], v[44:47]
	v_mfma_f32_16x16x32_bf16 v[40:43], v[212:215], v[166:169], v[40:43]
	v_mfma_f32_16x16x32_bf16 v[36:39], v[216:219], v[166:169], v[36:39]
	v_mfma_f32_16x16x32_bf16 v[32:35], v[220:223], v[166:169], v[32:35]
	ds_read_b128 v[134:137], v126
	ds_read_b128 v[138:141], v126 offset:1024
	ds_read_b128 v[154:157], v126 offset:2048
	ds_read_b128 v[158:161], v126 offset:3072
	ds_read_b128 v[162:165], v126 offset:4096
	ds_read_b128 v[166:169], v126 offset:5120
	v_or_b32_e32 v126, s10, v149
	v_add_u32_e32 v126, v126, v148
	v_mfma_f32_16x16x32_bf16 v[28:31], v[208:211], v[200:203], v[28:31]
	v_mfma_f32_16x16x32_bf16 v[24:27], v[212:215], v[200:203], v[24:27]
	v_mfma_f32_16x16x32_bf16 v[20:23], v[216:219], v[200:203], v[20:23]
	v_mfma_f32_16x16x32_bf16 v[16:19], v[220:223], v[200:203], v[16:19]
	v_mfma_f32_16x16x32_bf16 v[8:11], v[208:211], v[204:207], v[8:11]
	v_mfma_f32_16x16x32_bf16 v[4:7], v[212:215], v[204:207], v[4:7]
	v_mfma_f32_16x16x32_bf16 v[12:15], v[216:219], v[204:207], v[12:15]
	v_mfma_f32_16x16x32_bf16 v[0:3], v[220:223], v[204:207], v[0:3]
	ds_read_b128 v[200:203], v126 offset:12288
	ds_read_b128 v[204:207], v126 offset:13312
	ds_read_b128 v[208:211], v126 offset:14336
	ds_read_b128 v[212:215], v126 offset:15360
	s_waitcnt lgkmcnt(0)
	v_mfma_f32_16x16x32_bf16 v[92:95], v[200:203], v[134:137], v[92:95]
	v_mfma_f32_16x16x32_bf16 v[88:91], v[204:207], v[134:137], v[88:91]
	v_mfma_f32_16x16x32_bf16 v[84:87], v[208:211], v[134:137], v[84:87]
	v_mfma_f32_16x16x32_bf16 v[80:83], v[212:215], v[134:137], v[80:83]
	v_mfma_f32_16x16x32_bf16 v[76:79], v[200:203], v[138:141], v[76:79]
	v_mfma_f32_16x16x32_bf16 v[72:75], v[204:207], v[138:141], v[72:75]
	v_mfma_f32_16x16x32_bf16 v[68:71], v[208:211], v[138:141], v[68:71]
	v_mfma_f32_16x16x32_bf16 v[64:67], v[212:215], v[138:141], v[64:67]
	v_mfma_f32_16x16x32_bf16 v[60:63], v[200:203], v[154:157], v[60:63]
	v_mfma_f32_16x16x32_bf16 v[56:59], v[204:207], v[154:157], v[56:59]
	v_mfma_f32_16x16x32_bf16 v[52:55], v[208:211], v[154:157], v[52:55]
	v_mfma_f32_16x16x32_bf16 v[48:51], v[212:215], v[154:157], v[48:51]
	v_mfma_f32_16x16x32_bf16 v[44:47], v[200:203], v[158:161], v[44:47]
	v_mfma_f32_16x16x32_bf16 v[40:43], v[204:207], v[158:161], v[40:43]
	v_mfma_f32_16x16x32_bf16 v[36:39], v[208:211], v[158:161], v[36:39]
	v_mfma_f32_16x16x32_bf16 v[32:35], v[212:215], v[158:161], v[32:35]
	v_mfma_f32_16x16x32_bf16 v[28:31], v[200:203], v[162:165], v[28:31]
	v_mfma_f32_16x16x32_bf16 v[24:27], v[204:207], v[162:165], v[24:27]
	v_mfma_f32_16x16x32_bf16 v[20:23], v[208:211], v[162:165], v[20:23]
	v_mfma_f32_16x16x32_bf16 v[16:19], v[212:215], v[162:165], v[16:19]
	v_mfma_f32_16x16x32_bf16 v[8:11], v[200:203], v[166:169], v[8:11]
	v_mfma_f32_16x16x32_bf16 v[4:7], v[204:207], v[166:169], v[4:7]
	v_mfma_f32_16x16x32_bf16 v[12:15], v[208:211], v[166:169], v[12:15]
	v_mfma_f32_16x16x32_bf16 v[0:3], v[212:215], v[166:169], v[0:3]
	s_cbranch_scc0 .LBB0_53
	v_add_u32_e32 v170, v147, v128
	v_add_u32_e32 v172, v149, v148
	s_waitcnt vmcnt(5)
	s_barrier
	ds_read_b128 v[116:119], v170 offset:40960
	ds_read_b128 v[120:123], v170 offset:41984
	ds_read_b128 v[124:127], v170 offset:43008
	ds_read_b128 v[134:137], v170 offset:44032
	ds_read_b128 v[138:141], v170 offset:45056
	ds_read_b128 v[154:157], v170 offset:46080
	ds_read_b128 v[158:161], v172 offset:53248
	ds_read_b128 v[162:165], v172 offset:54272
	ds_read_b128 v[166:169], v172 offset:55296
	ds_read_b128 v[200:203], v172 offset:56320
	s_waitcnt lgkmcnt(0)
	v_mfma_f32_16x16x32_bf16 v[92:95], v[158:161], v[116:119], v[92:95]
	s_waitcnt vmcnt(0)
	s_barrier
	s_mulk_i32 s7, 0xc0
	v_mfma_f32_16x16x32_bf16 v[88:91], v[162:165], v[116:119], v[88:91]
	v_readlane_b32 s8, v243, 5
	v_readlane_b32 s14, v243, 11
	v_readlane_b32 s15, v243, 12
	v_mfma_f32_16x16x32_bf16 v[84:87], v[166:169], v[116:119], v[84:87]
	v_readlane_b32 s9, v243, 6
	v_readlane_b32 s10, v243, 7
	v_readlane_b32 s11, v243, 8
	v_mfma_f32_16x16x32_bf16 v[80:83], v[200:203], v[116:119], v[80:83]
	v_readlane_b32 s12, v243, 9
	v_readlane_b32 s13, v243, 10
	v_readlane_b32 s16, v243, 13
	v_mfma_f32_16x16x32_bf16 v[76:79], v[158:161], v[120:123], v[76:79]
	v_readlane_b32 s17, v243, 14
	v_readlane_b32 s18, v243, 15
	v_readlane_b32 s19, v243, 16
	v_mfma_f32_16x16x32_bf16 v[72:75], v[162:165], v[120:123], v[72:75]
	v_readlane_b32 s20, v243, 17
	v_readlane_b32 s21, v243, 18
	v_readlane_b32 s22, v243, 19
	v_mfma_f32_16x16x32_bf16 v[68:71], v[166:169], v[120:123], v[68:71]
	v_readlane_b32 s23, v243, 20
	s_mov_b64 s[24:25], 0x5000
	s_add_i32 s5, s5, s51
	v_mfma_f32_16x16x32_bf16 v[64:67], v[200:203], v[120:123], v[64:67]
	s_cmpk_gt_i32 s5, 0xff
	v_mfma_f32_16x16x32_bf16 v[60:63], v[158:161], v[124:127], v[60:63]
	v_mfma_f32_16x16x32_bf16 v[56:59], v[162:165], v[124:127], v[56:59]
	v_mfma_f32_16x16x32_bf16 v[52:55], v[166:169], v[124:127], v[52:55]
	v_mfma_f32_16x16x32_bf16 v[48:51], v[200:203], v[124:127], v[48:51]
	v_mfma_f32_16x16x32_bf16 v[44:47], v[158:161], v[134:137], v[44:47]
	v_mfma_f32_16x16x32_bf16 v[40:43], v[162:165], v[134:137], v[40:43]
	v_mfma_f32_16x16x32_bf16 v[36:39], v[166:169], v[134:137], v[36:39]
	v_mfma_f32_16x16x32_bf16 v[32:35], v[200:203], v[134:137], v[32:35]
	v_mfma_f32_16x16x32_bf16 v[28:31], v[158:161], v[138:141], v[28:31]
	v_mfma_f32_16x16x32_bf16 v[24:27], v[162:165], v[138:141], v[24:27]
	v_mfma_f32_16x16x32_bf16 v[20:23], v[166:169], v[138:141], v[20:23]
	v_mfma_f32_16x16x32_bf16 v[16:19], v[200:203], v[138:141], v[16:19]
	v_mfma_f32_16x16x32_bf16 v[8:11], v[158:161], v[154:157], v[8:11]
	v_mfma_f32_16x16x32_bf16 v[4:7], v[162:165], v[154:157], v[4:7]
	v_mfma_f32_16x16x32_bf16 v[116:119], v[166:169], v[154:157], v[12:15]
	v_mfma_f32_16x16x32_bf16 v[0:3], v[200:203], v[154:157], v[0:3]
	s_nop 1
	ds_read_b128 v[12:15], v170
	ds_read_b128 v[120:123], v170 offset:1024
	ds_read_b128 v[124:127], v170 offset:2048
	ds_read_b128 v[134:137], v170 offset:3072
	ds_read_b128 v[138:141], v170 offset:4096
	ds_read_b128 v[154:157], v170 offset:5120
	ds_read_b128 v[158:161], v172 offset:12288
	ds_read_b128 v[162:165], v172 offset:13312
	ds_read_b128 v[166:169], v172 offset:14336
	ds_read_b128 v[200:203], v172 offset:15360
	s_waitcnt lgkmcnt(0)
	v_mfma_f32_16x16x32_bf16 v[76:79], v[158:161], v[120:123], v[76:79]
	v_mfma_f32_16x16x32_bf16 v[72:75], v[162:165], v[120:123], v[72:75]
	v_mfma_f32_16x16x32_bf16 v[68:71], v[166:169], v[120:123], v[68:71]
	v_mfma_f32_16x16x32_bf16 v[64:67], v[200:203], v[120:123], v[64:67]
	v_mfma_f32_16x16x32_bf16 v[204:207], v[158:161], v[12:15], v[92:95]
	v_mfma_f32_16x16x32_bf16 v[88:91], v[162:165], v[12:15], v[88:91]
	v_mfma_f32_16x16x32_bf16 v[84:87], v[166:169], v[12:15], v[84:87]
	v_mfma_f32_16x16x32_bf16 v[80:83], v[200:203], v[12:15], v[80:83]
	v_mfma_f32_16x16x32_bf16 v[12:15], v[158:161], v[154:157], v[8:11]
	v_mfma_f32_16x16x32_bf16 v[8:11], v[162:165], v[154:157], v[4:7]
	v_mfma_f32_16x16x32_bf16 v[4:7], v[166:169], v[154:157], v[116:119]
	v_mfma_f32_16x16x32_bf16 v[28:31], v[158:161], v[138:141], v[28:31]
	v_mfma_f32_16x16x32_bf16 v[24:27], v[162:165], v[138:141], v[24:27]
	v_mfma_f32_16x16x32_bf16 v[20:23], v[166:169], v[138:141], v[20:23]
	v_mfma_f32_16x16x32_bf16 v[16:19], v[200:203], v[138:141], v[16:19]
	v_mfma_f32_16x16x32_bf16 v[60:63], v[158:161], v[124:127], v[60:63]
	v_mfma_f32_16x16x32_bf16 v[56:59], v[162:165], v[124:127], v[56:59]
	v_mfma_f32_16x16x32_bf16 v[52:55], v[166:169], v[124:127], v[52:55]
	v_mfma_f32_16x16x32_bf16 v[48:51], v[200:203], v[124:127], v[48:51]
	v_mfma_f32_16x16x32_bf16 v[44:47], v[158:161], v[134:137], v[44:47]
	v_mfma_f32_16x16x32_bf16 v[40:43], v[162:165], v[134:137], v[40:43]
	v_mfma_f32_16x16x32_bf16 v[36:39], v[166:169], v[134:137], v[36:39]
	v_mfma_f32_16x16x32_bf16 v[32:35], v[200:203], v[134:137], v[32:35]
	v_mfma_f32_16x16x32_bf16 v[0:3], v[200:203], v[154:157], v[0:3]
	v_readlane_b32 s10, v242, 27
	v_readlane_b32 s11, v242, 28
	v_readlane_b32 s12, v242, 29
	v_readlane_b32 s13, v242, 30
	v_readlane_b32 s14, v243, 11
	v_readlane_b32 s15, v243, 12
	s_mov_b32 s8, 0x3fd744fd
	v_add_u32_e32 v236, s7, v145
	v_or_b32_e32 v254, s6, v146
	v_mov_b32_e32 v255, 0
	v_or_b32_e32 v237, v236, v133
	v_lshlrev_b64 v[254:255], 2, v[254:255]
	s_nop 0
	v_lshl_add_u64 v[250:251], s[12:13], 0, v[254:255]
	v_lshl_add_u64 v[252:253], s[14:15], 0, v[254:255]
	s_mov_b64 s[14:15], 0x5000
	v_lshl_add_u64 v[252:253], v[252:253], 0, s[14:15]
	v_readlane_b32 s12, v241, 9
	s_add_i32 s12, s12, -10
	s_mul_i32 s12, s12, 57
	s_lshr_b32 s12, s12, 9
	s_lshl_b32 s12, s12, 12
	v_readlane_b32 s14, v243, 59
	v_readlane_b32 s15, v243, 60
	s_add_u32 s14, s14, s12
	s_addc_u32 s15, s15, 0
	v_lshl_add_u64 v[248:249], s[14:15], 0, v[254:255]
	v_readlane_b32 s14, v243, 61
	v_readlane_b32 s15, v243, 62
	s_add_u32 s14, s14, s12
	s_addc_u32 s15, s15, 0
	v_lshl_add_u64 v[254:255], s[14:15], 0, v[254:255]
	global_load_dwordx4 v[96:99], v[248:249], off
	global_load_dwordx4 v[112:115], v[254:255], off
	global_load_dwordx4 v[100:103], v[248:249], off offset:64
	global_load_dwordx4 v[150:153], v[254:255], off offset:64
	global_load_dwordx4 v[104:107], v[248:249], off offset:128
	global_load_dwordx4 v[142:145], v[254:255], off offset:128
	global_load_dwordx4 v[108:111], v[248:249], off offset:192
	global_load_dwordx4 v[146:149], v[254:255], off offset:192
	v_mov_b32_e32 v255, 0
	v_add_u32_e32 v254, 0, v237
	v_add_u32_e32 v236, 0xfffff000, v254
	v_cmp_lt_i32_e32 vcc, 0xfff, v254
	v_lshrrev_b32_e32 v236, 10, v236
	v_lshlrev_b32_e32 v248, 3, v254
	v_lshlrev_b32_e32 v254, 12, v254
	v_add_u32_e32 v236, 1, v236
	v_mov_b32_e32 v249, 0
	v_cndmask_b32_e32 v236, 0, v236, vcc
	v_lshl_add_u64 v[224:225], v[248:249], 0, s[10:11]
	v_lshl_add_u64 v[228:229], v[254:255], 0, v[250:251]
	v_add_u32_e32 v236, s4, v236
	v_mad_i64_i32 v[232:233], s[0:1], v236, s33, v[252:253]
	global_load_dwordx2 v[132:133], v[224:225], off
	v_add_u32_e32 v254, 16, v237
	v_add_u32_e32 v236, 0xfffff000, v254
	v_cmp_lt_i32_e32 vcc, 0xfff, v254
	v_lshrrev_b32_e32 v236, 10, v236
	v_lshlrev_b32_e32 v248, 3, v254
	v_lshlrev_b32_e32 v254, 12, v254
	v_add_u32_e32 v236, 1, v236
	v_mov_b32_e32 v249, 0
	v_cndmask_b32_e32 v236, 0, v236, vcc
	v_lshl_add_u64 v[226:227], v[248:249], 0, s[10:11]
	v_lshl_add_u64 v[230:231], v[254:255], 0, v[250:251]
	v_add_u32_e32 v236, s4, v236
	v_mad_i64_i32 v[234:235], s[0:1], v236, s33, v[252:253]
	global_load_dword v128, v[226:227], off
	global_load_dword v170, v[226:227], off offset:4
	global_load_dwordx4 v[154:157], v[228:229], off
	global_load_dwordx4 v[116:119], v[232:233], off
	global_load_dwordx4 v[158:161], v[228:229], off offset:64
	global_load_dwordx4 v[120:123], v[232:233], off offset:64
	global_load_dwordx4 v[162:165], v[228:229], off offset:128
	global_load_dwordx4 v[124:127], v[232:233], off offset:128
	global_load_dwordx4 v[166:169], v[228:229], off offset:192
	global_load_dwordx4 v[134:137], v[232:233], off offset:192
	global_load_dwordx4 v[208:211], v[230:231], off
	global_load_dwordx4 v[138:141], v[234:235], off
	global_load_dwordx4 v[212:215], v[230:231], off offset:64
	global_load_dwordx4 v[200:203], v[234:235], off offset:64
	global_load_dwordx4 v[216:219], v[230:231], off offset:128
	global_load_dwordx4 v[92:95], v[234:235], off offset:128
	global_load_dwordx4 v[220:223], v[230:231], off offset:192
	global_load_dwordx4 v[244:247], v[234:235], off offset:192
	s_waitcnt vmcnt(0)
	v_pk_mul_f32 v[204:205], v[204:205], v[116:117]
	v_pk_add_f32 v[154:155], v[154:155], v[132:133] op_sel_hi:[1,0] neg_lo:[0,1] neg_hi:[0,1]
	v_pk_mul_f32 v[206:207], v[206:207], v[118:119]
	v_pk_add_f32 v[156:157], v[156:157], v[132:133] op_sel_hi:[1,0] neg_lo:[0,1] neg_hi:[0,1]
	v_pk_mul_f32 v[154:155], v[154:155], v[132:133] op_sel:[0,1] op_sel_hi:[1,1]
	v_pk_mul_f32 v[156:157], v[156:157], v[132:133] op_sel:[0,1] op_sel_hi:[1,1]
	v_pk_fma_f32 v[154:155], v[96:97], v[154:155], v[112:113]
	v_pk_fma_f32 v[156:157], v[98:99], v[156:157], v[114:115]
	v_pk_fma_f32 v[204:205], v[154:155], s[8:9], v[204:205] op_sel_hi:[1,0,1]
	v_pk_fma_f32 v[206:207], v[156:157], s[8:9], v[206:207] op_sel_hi:[1,0,1]
	global_store_dwordx4 v[228:229], v[204:207], off
	v_pk_mul_f32 v[88:89], v[88:89], v[120:121]
	v_pk_add_f32 v[158:159], v[158:159], v[132:133] op_sel_hi:[1,0] neg_lo:[0,1] neg_hi:[0,1]
	v_pk_mul_f32 v[90:91], v[90:91], v[122:123]
	v_pk_add_f32 v[160:161], v[160:161], v[132:133] op_sel_hi:[1,0] neg_lo:[0,1] neg_hi:[0,1]
	v_pk_mul_f32 v[158:159], v[158:159], v[132:133] op_sel:[0,1] op_sel_hi:[1,1]
	v_pk_mul_f32 v[160:161], v[160:161], v[132:133] op_sel:[0,1] op_sel_hi:[1,1]
	v_pk_fma_f32 v[158:159], v[100:101], v[158:159], v[150:151]
	v_pk_fma_f32 v[160:161], v[102:103], v[160:161], v[152:153]
	v_pk_fma_f32 v[88:89], v[158:159], s[8:9], v[88:89] op_sel_hi:[1,0,1]
	v_pk_fma_f32 v[90:91], v[160:161], s[8:9], v[90:91] op_sel_hi:[1,0,1]
	global_store_dwordx4 v[228:229], v[88:91], off offset:64
	v_pk_mul_f32 v[84:85], v[84:85], v[124:125]
	v_pk_add_f32 v[162:163], v[162:163], v[132:133] op_sel_hi:[1,0] neg_lo:[0,1] neg_hi:[0,1]
	v_pk_mul_f32 v[86:87], v[86:87], v[126:127]
	v_pk_add_f32 v[164:165], v[164:165], v[132:133] op_sel_hi:[1,0] neg_lo:[0,1] neg_hi:[0,1]
	v_pk_mul_f32 v[162:163], v[162:163], v[132:133] op_sel:[0,1] op_sel_hi:[1,1]
	v_pk_mul_f32 v[164:165], v[164:165], v[132:133] op_sel:[0,1] op_sel_hi:[1,1]
	v_pk_fma_f32 v[162:163], v[104:105], v[162:163], v[142:143]
	v_pk_fma_f32 v[164:165], v[106:107], v[164:165], v[144:145]
	v_pk_fma_f32 v[84:85], v[162:163], s[8:9], v[84:85] op_sel_hi:[1,0,1]
	v_pk_fma_f32 v[86:87], v[164:165], s[8:9], v[86:87] op_sel_hi:[1,0,1]
	global_store_dwordx4 v[228:229], v[84:87], off offset:128
	v_pk_mul_f32 v[80:81], v[80:81], v[134:135]
	v_pk_add_f32 v[166:167], v[166:167], v[132:133] op_sel_hi:[1,0] neg_lo:[0,1] neg_hi:[0,1]
	v_pk_mul_f32 v[82:83], v[82:83], v[136:137]
	v_pk_add_f32 v[168:169], v[168:169], v[132:133] op_sel_hi:[1,0] neg_lo:[0,1] neg_hi:[0,1]
	v_pk_mul_f32 v[166:167], v[166:167], v[132:133] op_sel:[0,1] op_sel_hi:[1,1]
	v_pk_mul_f32 v[168:169], v[168:169], v[132:133] op_sel:[0,1] op_sel_hi:[1,1]
	v_pk_fma_f32 v[166:167], v[108:109], v[166:167], v[146:147]
	v_pk_fma_f32 v[168:169], v[110:111], v[168:169], v[148:149]
	v_pk_fma_f32 v[80:81], v[166:167], s[8:9], v[80:81] op_sel_hi:[1,0,1]
	v_pk_fma_f32 v[82:83], v[168:169], s[8:9], v[82:83] op_sel_hi:[1,0,1]
	global_store_dwordx4 v[228:229], v[80:83], off offset:192
	v_pk_mul_f32 v[76:77], v[76:77], v[138:139]
	v_pk_add_f32 v[208:209], v[208:209], v[128:129] op_sel_hi:[1,0] neg_lo:[0,1] neg_hi:[0,1]
	v_pk_mul_f32 v[78:79], v[78:79], v[140:141]
	v_pk_add_f32 v[210:211], v[210:211], v[128:129] op_sel_hi:[1,0] neg_lo:[0,1] neg_hi:[0,1]
	v_pk_mul_f32 v[208:209], v[208:209], v[170:171] op_sel_hi:[1,0]
	v_pk_mul_f32 v[210:211], v[210:211], v[170:171] op_sel_hi:[1,0]
	v_pk_fma_f32 v[208:209], v[96:97], v[208:209], v[112:113]
	v_pk_fma_f32 v[210:211], v[98:99], v[210:211], v[114:115]
	v_pk_fma_f32 v[76:77], v[208:209], s[8:9], v[76:77] op_sel_hi:[1,0,1]
	v_pk_fma_f32 v[78:79], v[210:211], s[8:9], v[78:79] op_sel_hi:[1,0,1]
	global_store_dwordx4 v[230:231], v[76:79], off
	v_pk_mul_f32 v[72:73], v[72:73], v[200:201]
	v_pk_add_f32 v[212:213], v[212:213], v[128:129] op_sel_hi:[1,0] neg_lo:[0,1] neg_hi:[0,1]
	v_pk_mul_f32 v[74:75], v[74:75], v[202:203]
	v_pk_add_f32 v[214:215], v[214:215], v[128:129] op_sel_hi:[1,0] neg_lo:[0,1] neg_hi:[0,1]
	v_pk_mul_f32 v[212:213], v[212:213], v[170:171] op_sel_hi:[1,0]
	v_pk_mul_f32 v[214:215], v[214:215], v[170:171] op_sel_hi:[1,0]
	v_pk_fma_f32 v[212:213], v[100:101], v[212:213], v[150:151]
	v_pk_fma_f32 v[214:215], v[102:103], v[214:215], v[152:153]
	v_pk_fma_f32 v[72:73], v[212:213], s[8:9], v[72:73] op_sel_hi:[1,0,1]
	v_pk_fma_f32 v[74:75], v[214:215], s[8:9], v[74:75] op_sel_hi:[1,0,1]
	global_store_dwordx4 v[230:231], v[72:75], off offset:64
	v_pk_mul_f32 v[68:69], v[68:69], v[92:93]
	v_pk_add_f32 v[216:217], v[216:217], v[128:129] op_sel_hi:[1,0] neg_lo:[0,1] neg_hi:[0,1]
	v_pk_mul_f32 v[70:71], v[70:71], v[94:95]
	v_pk_add_f32 v[218:219], v[218:219], v[128:129] op_sel_hi:[1,0] neg_lo:[0,1] neg_hi:[0,1]
	v_pk_mul_f32 v[216:217], v[216:217], v[170:171] op_sel_hi:[1,0]
	v_pk_mul_f32 v[218:219], v[218:219], v[170:171] op_sel_hi:[1,0]
	v_pk_fma_f32 v[216:217], v[104:105], v[216:217], v[142:143]
	v_pk_fma_f32 v[218:219], v[106:107], v[218:219], v[144:145]
	v_pk_fma_f32 v[68:69], v[216:217], s[8:9], v[68:69] op_sel_hi:[1,0,1]
	v_pk_fma_f32 v[70:71], v[218:219], s[8:9], v[70:71] op_sel_hi:[1,0,1]
	global_store_dwordx4 v[230:231], v[68:71], off offset:128
	v_pk_mul_f32 v[64:65], v[64:65], v[244:245]
	v_pk_add_f32 v[220:221], v[220:221], v[128:129] op_sel_hi:[1,0] neg_lo:[0,1] neg_hi:[0,1]
	v_pk_mul_f32 v[66:67], v[66:67], v[246:247]
	v_pk_add_f32 v[222:223], v[222:223], v[128:129] op_sel_hi:[1,0] neg_lo:[0,1] neg_hi:[0,1]
	v_pk_mul_f32 v[220:221], v[220:221], v[170:171] op_sel_hi:[1,0]
	v_pk_mul_f32 v[222:223], v[222:223], v[170:171] op_sel_hi:[1,0]
	v_pk_fma_f32 v[220:221], v[108:109], v[220:221], v[146:147]
	v_pk_fma_f32 v[222:223], v[110:111], v[222:223], v[148:149]
	v_pk_fma_f32 v[64:65], v[220:221], s[8:9], v[64:65] op_sel_hi:[1,0,1]
	v_pk_fma_f32 v[66:67], v[222:223], s[8:9], v[66:67] op_sel_hi:[1,0,1]
	global_store_dwordx4 v[230:231], v[64:67], off offset:192
	v_add_u32_e32 v254, 32, v237
	v_add_u32_e32 v236, 0xfffff000, v254
	v_cmp_lt_i32_e32 vcc, 0xfff, v254
	v_lshrrev_b32_e32 v236, 10, v236
	v_lshlrev_b32_e32 v248, 3, v254
	v_lshlrev_b32_e32 v254, 12, v254
	v_add_u32_e32 v236, 1, v236
	v_mov_b32_e32 v249, 0
	v_cndmask_b32_e32 v236, 0, v236, vcc
	v_lshl_add_u64 v[224:225], v[248:249], 0, s[10:11]
	v_lshl_add_u64 v[228:229], v[254:255], 0, v[250:251]
	v_add_u32_e32 v236, s4, v236
	v_mad_i64_i32 v[232:233], s[0:1], v236, s33, v[252:253]
	global_load_dwordx2 v[132:133], v[224:225], off
	v_add_u32_e32 v254, 48, v237
	v_add_u32_e32 v236, 0xfffff000, v254
	v_cmp_lt_i32_e32 vcc, 0xfff, v254
	v_lshrrev_b32_e32 v236, 10, v236
	v_lshlrev_b32_e32 v248, 3, v254
	v_lshlrev_b32_e32 v254, 12, v254
	v_add_u32_e32 v236, 1, v236
	v_mov_b32_e32 v249, 0
	v_cndmask_b32_e32 v236, 0, v236, vcc
	v_lshl_add_u64 v[226:227], v[248:249], 0, s[10:11]
	v_lshl_add_u64 v[230:231], v[254:255], 0, v[250:251]
	v_add_u32_e32 v236, s4, v236
	v_mad_i64_i32 v[234:235], s[0:1], v236, s33, v[252:253]
	global_load_dword v128, v[226:227], off
	global_load_dword v170, v[226:227], off offset:4
	global_load_dwordx4 v[154:157], v[228:229], off
	global_load_dwordx4 v[116:119], v[232:233], off
	global_load_dwordx4 v[158:161], v[228:229], off offset:64
	global_load_dwordx4 v[120:123], v[232:233], off offset:64
	global_load_dwordx4 v[162:165], v[228:229], off offset:128
	global_load_dwordx4 v[124:127], v[232:233], off offset:128
	global_load_dwordx4 v[166:169], v[228:229], off offset:192
	global_load_dwordx4 v[134:137], v[232:233], off offset:192
	global_load_dwordx4 v[208:211], v[230:231], off
	global_load_dwordx4 v[138:141], v[234:235], off
	global_load_dwordx4 v[212:215], v[230:231], off offset:64
	global_load_dwordx4 v[200:203], v[234:235], off offset:64
	global_load_dwordx4 v[216:219], v[230:231], off offset:128
	global_load_dwordx4 v[92:95], v[234:235], off offset:128
	global_load_dwordx4 v[220:223], v[230:231], off offset:192
	global_load_dwordx4 v[244:247], v[234:235], off offset:192
	s_waitcnt vmcnt(0)
	v_pk_mul_f32 v[60:61], v[60:61], v[116:117]
	v_pk_add_f32 v[154:155], v[154:155], v[132:133] op_sel_hi:[1,0] neg_lo:[0,1] neg_hi:[0,1]
	v_pk_mul_f32 v[62:63], v[62:63], v[118:119]
	v_pk_add_f32 v[156:157], v[156:157], v[132:133] op_sel_hi:[1,0] neg_lo:[0,1] neg_hi:[0,1]
	v_pk_mul_f32 v[154:155], v[154:155], v[132:133] op_sel:[0,1] op_sel_hi:[1,1]
	v_pk_mul_f32 v[156:157], v[156:157], v[132:133] op_sel:[0,1] op_sel_hi:[1,1]
	v_pk_fma_f32 v[154:155], v[96:97], v[154:155], v[112:113]
	v_pk_fma_f32 v[156:157], v[98:99], v[156:157], v[114:115]
	v_pk_fma_f32 v[60:61], v[154:155], s[8:9], v[60:61] op_sel_hi:[1,0,1]
	v_pk_fma_f32 v[62:63], v[156:157], s[8:9], v[62:63] op_sel_hi:[1,0,1]
	global_store_dwordx4 v[228:229], v[60:63], off
	v_pk_mul_f32 v[56:57], v[56:57], v[120:121]
	v_pk_add_f32 v[158:159], v[158:159], v[132:133] op_sel_hi:[1,0] neg_lo:[0,1] neg_hi:[0,1]
	v_pk_mul_f32 v[58:59], v[58:59], v[122:123]
	v_pk_add_f32 v[160:161], v[160:161], v[132:133] op_sel_hi:[1,0] neg_lo:[0,1] neg_hi:[0,1]
	v_pk_mul_f32 v[158:159], v[158:159], v[132:133] op_sel:[0,1] op_sel_hi:[1,1]
	v_pk_mul_f32 v[160:161], v[160:161], v[132:133] op_sel:[0,1] op_sel_hi:[1,1]
	v_pk_fma_f32 v[158:159], v[100:101], v[158:159], v[150:151]
	v_pk_fma_f32 v[160:161], v[102:103], v[160:161], v[152:153]
	v_pk_fma_f32 v[56:57], v[158:159], s[8:9], v[56:57] op_sel_hi:[1,0,1]
	v_pk_fma_f32 v[58:59], v[160:161], s[8:9], v[58:59] op_sel_hi:[1,0,1]
	global_store_dwordx4 v[228:229], v[56:59], off offset:64
	v_pk_mul_f32 v[52:53], v[52:53], v[124:125]
	v_pk_add_f32 v[162:163], v[162:163], v[132:133] op_sel_hi:[1,0] neg_lo:[0,1] neg_hi:[0,1]
	v_pk_mul_f32 v[54:55], v[54:55], v[126:127]
	v_pk_add_f32 v[164:165], v[164:165], v[132:133] op_sel_hi:[1,0] neg_lo:[0,1] neg_hi:[0,1]
	v_pk_mul_f32 v[162:163], v[162:163], v[132:133] op_sel:[0,1] op_sel_hi:[1,1]
	v_pk_mul_f32 v[164:165], v[164:165], v[132:133] op_sel:[0,1] op_sel_hi:[1,1]
	v_pk_fma_f32 v[162:163], v[104:105], v[162:163], v[142:143]
	v_pk_fma_f32 v[164:165], v[106:107], v[164:165], v[144:145]
	v_pk_fma_f32 v[52:53], v[162:163], s[8:9], v[52:53] op_sel_hi:[1,0,1]
	v_pk_fma_f32 v[54:55], v[164:165], s[8:9], v[54:55] op_sel_hi:[1,0,1]
	global_store_dwordx4 v[228:229], v[52:55], off offset:128
	v_pk_mul_f32 v[48:49], v[48:49], v[134:135]
	v_pk_add_f32 v[166:167], v[166:167], v[132:133] op_sel_hi:[1,0] neg_lo:[0,1] neg_hi:[0,1]
	v_pk_mul_f32 v[50:51], v[50:51], v[136:137]
	v_pk_add_f32 v[168:169], v[168:169], v[132:133] op_sel_hi:[1,0] neg_lo:[0,1] neg_hi:[0,1]
	v_pk_mul_f32 v[166:167], v[166:167], v[132:133] op_sel:[0,1] op_sel_hi:[1,1]
	v_pk_mul_f32 v[168:169], v[168:169], v[132:133] op_sel:[0,1] op_sel_hi:[1,1]
	v_pk_fma_f32 v[166:167], v[108:109], v[166:167], v[146:147]
	v_pk_fma_f32 v[168:169], v[110:111], v[168:169], v[148:149]
	v_pk_fma_f32 v[48:49], v[166:167], s[8:9], v[48:49] op_sel_hi:[1,0,1]
	v_pk_fma_f32 v[50:51], v[168:169], s[8:9], v[50:51] op_sel_hi:[1,0,1]
	global_store_dwordx4 v[228:229], v[48:51], off offset:192
	v_pk_mul_f32 v[44:45], v[44:45], v[138:139]
	v_pk_add_f32 v[208:209], v[208:209], v[128:129] op_sel_hi:[1,0] neg_lo:[0,1] neg_hi:[0,1]
	v_pk_mul_f32 v[46:47], v[46:47], v[140:141]
	v_pk_add_f32 v[210:211], v[210:211], v[128:129] op_sel_hi:[1,0] neg_lo:[0,1] neg_hi:[0,1]
	v_pk_mul_f32 v[208:209], v[208:209], v[170:171] op_sel_hi:[1,0]
	v_pk_mul_f32 v[210:211], v[210:211], v[170:171] op_sel_hi:[1,0]
	v_pk_fma_f32 v[208:209], v[96:97], v[208:209], v[112:113]
	v_pk_fma_f32 v[210:211], v[98:99], v[210:211], v[114:115]
	v_pk_fma_f32 v[44:45], v[208:209], s[8:9], v[44:45] op_sel_hi:[1,0,1]
	v_pk_fma_f32 v[46:47], v[210:211], s[8:9], v[46:47] op_sel_hi:[1,0,1]
	global_store_dwordx4 v[230:231], v[44:47], off
	v_pk_mul_f32 v[40:41], v[40:41], v[200:201]
	v_pk_add_f32 v[212:213], v[212:213], v[128:129] op_sel_hi:[1,0] neg_lo:[0,1] neg_hi:[0,1]
	v_pk_mul_f32 v[42:43], v[42:43], v[202:203]
	v_pk_add_f32 v[214:215], v[214:215], v[128:129] op_sel_hi:[1,0] neg_lo:[0,1] neg_hi:[0,1]
	v_pk_mul_f32 v[212:213], v[212:213], v[170:171] op_sel_hi:[1,0]
	v_pk_mul_f32 v[214:215], v[214:215], v[170:171] op_sel_hi:[1,0]
	v_pk_fma_f32 v[212:213], v[100:101], v[212:213], v[150:151]
	v_pk_fma_f32 v[214:215], v[102:103], v[214:215], v[152:153]
	v_pk_fma_f32 v[40:41], v[212:213], s[8:9], v[40:41] op_sel_hi:[1,0,1]
	v_pk_fma_f32 v[42:43], v[214:215], s[8:9], v[42:43] op_sel_hi:[1,0,1]
	global_store_dwordx4 v[230:231], v[40:43], off offset:64
	v_pk_mul_f32 v[36:37], v[36:37], v[92:93]
	v_pk_add_f32 v[216:217], v[216:217], v[128:129] op_sel_hi:[1,0] neg_lo:[0,1] neg_hi:[0,1]
	v_pk_mul_f32 v[38:39], v[38:39], v[94:95]
	v_pk_add_f32 v[218:219], v[218:219], v[128:129] op_sel_hi:[1,0] neg_lo:[0,1] neg_hi:[0,1]
	v_pk_mul_f32 v[216:217], v[216:217], v[170:171] op_sel_hi:[1,0]
	v_pk_mul_f32 v[218:219], v[218:219], v[170:171] op_sel_hi:[1,0]
	v_pk_fma_f32 v[216:217], v[104:105], v[216:217], v[142:143]
	v_pk_fma_f32 v[218:219], v[106:107], v[218:219], v[144:145]
	v_pk_fma_f32 v[36:37], v[216:217], s[8:9], v[36:37] op_sel_hi:[1,0,1]
	v_pk_fma_f32 v[38:39], v[218:219], s[8:9], v[38:39] op_sel_hi:[1,0,1]
	global_store_dwordx4 v[230:231], v[36:39], off offset:128
	v_pk_mul_f32 v[32:33], v[32:33], v[244:245]
	v_pk_add_f32 v[220:221], v[220:221], v[128:129] op_sel_hi:[1,0] neg_lo:[0,1] neg_hi:[0,1]
	v_pk_mul_f32 v[34:35], v[34:35], v[246:247]
	v_pk_add_f32 v[222:223], v[222:223], v[128:129] op_sel_hi:[1,0] neg_lo:[0,1] neg_hi:[0,1]
	v_pk_mul_f32 v[220:221], v[220:221], v[170:171] op_sel_hi:[1,0]
	v_pk_mul_f32 v[222:223], v[222:223], v[170:171] op_sel_hi:[1,0]
	v_pk_fma_f32 v[220:221], v[108:109], v[220:221], v[146:147]
	v_pk_fma_f32 v[222:223], v[110:111], v[222:223], v[148:149]
	v_pk_fma_f32 v[32:33], v[220:221], s[8:9], v[32:33] op_sel_hi:[1,0,1]
	v_pk_fma_f32 v[34:35], v[222:223], s[8:9], v[34:35] op_sel_hi:[1,0,1]
	global_store_dwordx4 v[230:231], v[32:35], off offset:192
	v_add_u32_e32 v254, 64, v237
	v_add_u32_e32 v236, 0xfffff000, v254
	v_cmp_lt_i32_e32 vcc, 0xfff, v254
	v_lshrrev_b32_e32 v236, 10, v236
	v_lshlrev_b32_e32 v248, 3, v254
	v_lshlrev_b32_e32 v254, 12, v254
	v_add_u32_e32 v236, 1, v236
	v_mov_b32_e32 v249, 0
	v_cndmask_b32_e32 v236, 0, v236, vcc
	v_lshl_add_u64 v[224:225], v[248:249], 0, s[10:11]
	v_lshl_add_u64 v[228:229], v[254:255], 0, v[250:251]
	v_add_u32_e32 v236, s4, v236
	v_mad_i64_i32 v[232:233], s[0:1], v236, s33, v[252:253]
	global_load_dwordx2 v[132:133], v[224:225], off
	v_add_u32_e32 v254, 80, v237
	v_add_u32_e32 v236, 0xfffff000, v254
	v_cmp_lt_i32_e32 vcc, 0xfff, v254
	v_lshrrev_b32_e32 v236, 10, v236
	v_lshlrev_b32_e32 v248, 3, v254
	v_lshlrev_b32_e32 v254, 12, v254
	v_add_u32_e32 v236, 1, v236
	v_mov_b32_e32 v249, 0
	v_cndmask_b32_e32 v236, 0, v236, vcc
	v_lshl_add_u64 v[226:227], v[248:249], 0, s[10:11]
	v_lshl_add_u64 v[230:231], v[254:255], 0, v[250:251]
	v_add_u32_e32 v236, s4, v236
	v_mad_i64_i32 v[234:235], s[0:1], v236, s33, v[252:253]
	global_load_dword v128, v[226:227], off
	global_load_dword v170, v[226:227], off offset:4
	global_load_dwordx4 v[154:157], v[228:229], off
	global_load_dwordx4 v[116:119], v[232:233], off
	global_load_dwordx4 v[158:161], v[228:229], off offset:64
	global_load_dwordx4 v[120:123], v[232:233], off offset:64
	global_load_dwordx4 v[162:165], v[228:229], off offset:128
	global_load_dwordx4 v[124:127], v[232:233], off offset:128
	global_load_dwordx4 v[166:169], v[228:229], off offset:192
	global_load_dwordx4 v[134:137], v[232:233], off offset:192
	global_load_dwordx4 v[208:211], v[230:231], off
	global_load_dwordx4 v[138:141], v[234:235], off
	global_load_dwordx4 v[212:215], v[230:231], off offset:64
	global_load_dwordx4 v[200:203], v[234:235], off offset:64
	global_load_dwordx4 v[216:219], v[230:231], off offset:128
	global_load_dwordx4 v[92:95], v[234:235], off offset:128
	global_load_dwordx4 v[220:223], v[230:231], off offset:192
	global_load_dwordx4 v[244:247], v[234:235], off offset:192
	s_waitcnt vmcnt(0)
	v_pk_mul_f32 v[28:29], v[28:29], v[116:117]
	v_pk_add_f32 v[154:155], v[154:155], v[132:133] op_sel_hi:[1,0] neg_lo:[0,1] neg_hi:[0,1]
	v_pk_mul_f32 v[30:31], v[30:31], v[118:119]
	v_pk_add_f32 v[156:157], v[156:157], v[132:133] op_sel_hi:[1,0] neg_lo:[0,1] neg_hi:[0,1]
	v_pk_mul_f32 v[154:155], v[154:155], v[132:133] op_sel:[0,1] op_sel_hi:[1,1]
	v_pk_mul_f32 v[156:157], v[156:157], v[132:133] op_sel:[0,1] op_sel_hi:[1,1]
	v_pk_fma_f32 v[154:155], v[96:97], v[154:155], v[112:113]
	v_pk_fma_f32 v[156:157], v[98:99], v[156:157], v[114:115]
	v_pk_fma_f32 v[28:29], v[154:155], s[8:9], v[28:29] op_sel_hi:[1,0,1]
	v_pk_fma_f32 v[30:31], v[156:157], s[8:9], v[30:31] op_sel_hi:[1,0,1]
	global_store_dwordx4 v[228:229], v[28:31], off
	v_pk_mul_f32 v[24:25], v[24:25], v[120:121]
	v_pk_add_f32 v[158:159], v[158:159], v[132:133] op_sel_hi:[1,0] neg_lo:[0,1] neg_hi:[0,1]
	v_pk_mul_f32 v[26:27], v[26:27], v[122:123]
	v_pk_add_f32 v[160:161], v[160:161], v[132:133] op_sel_hi:[1,0] neg_lo:[0,1] neg_hi:[0,1]
	v_pk_mul_f32 v[158:159], v[158:159], v[132:133] op_sel:[0,1] op_sel_hi:[1,1]
	v_pk_mul_f32 v[160:161], v[160:161], v[132:133] op_sel:[0,1] op_sel_hi:[1,1]
	v_pk_fma_f32 v[158:159], v[100:101], v[158:159], v[150:151]
	v_pk_fma_f32 v[160:161], v[102:103], v[160:161], v[152:153]
	v_pk_fma_f32 v[24:25], v[158:159], s[8:9], v[24:25] op_sel_hi:[1,0,1]
	v_pk_fma_f32 v[26:27], v[160:161], s[8:9], v[26:27] op_sel_hi:[1,0,1]
	global_store_dwordx4 v[228:229], v[24:27], off offset:64
	v_pk_mul_f32 v[20:21], v[20:21], v[124:125]
	v_pk_add_f32 v[162:163], v[162:163], v[132:133] op_sel_hi:[1,0] neg_lo:[0,1] neg_hi:[0,1]
	v_pk_mul_f32 v[22:23], v[22:23], v[126:127]
	v_pk_add_f32 v[164:165], v[164:165], v[132:133] op_sel_hi:[1,0] neg_lo:[0,1] neg_hi:[0,1]
	v_pk_mul_f32 v[162:163], v[162:163], v[132:133] op_sel:[0,1] op_sel_hi:[1,1]
	v_pk_mul_f32 v[164:165], v[164:165], v[132:133] op_sel:[0,1] op_sel_hi:[1,1]
	v_pk_fma_f32 v[162:163], v[104:105], v[162:163], v[142:143]
	v_pk_fma_f32 v[164:165], v[106:107], v[164:165], v[144:145]
	v_pk_fma_f32 v[20:21], v[162:163], s[8:9], v[20:21] op_sel_hi:[1,0,1]
	v_pk_fma_f32 v[22:23], v[164:165], s[8:9], v[22:23] op_sel_hi:[1,0,1]
	global_store_dwordx4 v[228:229], v[20:23], off offset:128
	v_pk_mul_f32 v[16:17], v[16:17], v[134:135]
	v_pk_add_f32 v[166:167], v[166:167], v[132:133] op_sel_hi:[1,0] neg_lo:[0,1] neg_hi:[0,1]
	v_pk_mul_f32 v[18:19], v[18:19], v[136:137]
	v_pk_add_f32 v[168:169], v[168:169], v[132:133] op_sel_hi:[1,0] neg_lo:[0,1] neg_hi:[0,1]
	v_pk_mul_f32 v[166:167], v[166:167], v[132:133] op_sel:[0,1] op_sel_hi:[1,1]
	v_pk_mul_f32 v[168:169], v[168:169], v[132:133] op_sel:[0,1] op_sel_hi:[1,1]
	v_pk_fma_f32 v[166:167], v[108:109], v[166:167], v[146:147]
	v_pk_fma_f32 v[168:169], v[110:111], v[168:169], v[148:149]
	v_pk_fma_f32 v[16:17], v[166:167], s[8:9], v[16:17] op_sel_hi:[1,0,1]
	v_pk_fma_f32 v[18:19], v[168:169], s[8:9], v[18:19] op_sel_hi:[1,0,1]
	global_store_dwordx4 v[228:229], v[16:19], off offset:192
	v_pk_mul_f32 v[12:13], v[12:13], v[138:139]
	v_pk_add_f32 v[208:209], v[208:209], v[128:129] op_sel_hi:[1,0] neg_lo:[0,1] neg_hi:[0,1]
	v_pk_mul_f32 v[14:15], v[14:15], v[140:141]
	v_pk_add_f32 v[210:211], v[210:211], v[128:129] op_sel_hi:[1,0] neg_lo:[0,1] neg_hi:[0,1]
	v_pk_mul_f32 v[208:209], v[208:209], v[170:171] op_sel_hi:[1,0]
	v_pk_mul_f32 v[210:211], v[210:211], v[170:171] op_sel_hi:[1,0]
	v_pk_fma_f32 v[208:209], v[96:97], v[208:209], v[112:113]
	v_pk_fma_f32 v[210:211], v[98:99], v[210:211], v[114:115]
	v_pk_fma_f32 v[12:13], v[208:209], s[8:9], v[12:13] op_sel_hi:[1,0,1]
	v_pk_fma_f32 v[14:15], v[210:211], s[8:9], v[14:15] op_sel_hi:[1,0,1]
	global_store_dwordx4 v[230:231], v[12:15], off
	v_pk_mul_f32 v[8:9], v[8:9], v[200:201]
	v_pk_add_f32 v[212:213], v[212:213], v[128:129] op_sel_hi:[1,0] neg_lo:[0,1] neg_hi:[0,1]
	v_pk_mul_f32 v[10:11], v[10:11], v[202:203]
	v_pk_add_f32 v[214:215], v[214:215], v[128:129] op_sel_hi:[1,0] neg_lo:[0,1] neg_hi:[0,1]
	v_pk_mul_f32 v[212:213], v[212:213], v[170:171] op_sel_hi:[1,0]
	v_pk_mul_f32 v[214:215], v[214:215], v[170:171] op_sel_hi:[1,0]
	v_pk_fma_f32 v[212:213], v[100:101], v[212:213], v[150:151]
	v_pk_fma_f32 v[214:215], v[102:103], v[214:215], v[152:153]
	v_pk_fma_f32 v[8:9], v[212:213], s[8:9], v[8:9] op_sel_hi:[1,0,1]
	v_pk_fma_f32 v[10:11], v[214:215], s[8:9], v[10:11] op_sel_hi:[1,0,1]
	global_store_dwordx4 v[230:231], v[8:11], off offset:64
	v_pk_mul_f32 v[4:5], v[4:5], v[92:93]
	v_pk_add_f32 v[216:217], v[216:217], v[128:129] op_sel_hi:[1,0] neg_lo:[0,1] neg_hi:[0,1]
	v_pk_mul_f32 v[6:7], v[6:7], v[94:95]
	v_pk_add_f32 v[218:219], v[218:219], v[128:129] op_sel_hi:[1,0] neg_lo:[0,1] neg_hi:[0,1]
	v_pk_mul_f32 v[216:217], v[216:217], v[170:171] op_sel_hi:[1,0]
	v_pk_mul_f32 v[218:219], v[218:219], v[170:171] op_sel_hi:[1,0]
	v_pk_fma_f32 v[216:217], v[104:105], v[216:217], v[142:143]
	v_pk_fma_f32 v[218:219], v[106:107], v[218:219], v[144:145]
	v_pk_fma_f32 v[4:5], v[216:217], s[8:9], v[4:5] op_sel_hi:[1,0,1]
	v_pk_fma_f32 v[6:7], v[218:219], s[8:9], v[6:7] op_sel_hi:[1,0,1]
	global_store_dwordx4 v[230:231], v[4:7], off offset:128
	v_pk_mul_f32 v[0:1], v[0:1], v[244:245]
	v_pk_add_f32 v[220:221], v[220:221], v[128:129] op_sel_hi:[1,0] neg_lo:[0,1] neg_hi:[0,1]
	v_pk_mul_f32 v[2:3], v[2:3], v[246:247]
	v_pk_add_f32 v[222:223], v[222:223], v[128:129] op_sel_hi:[1,0] neg_lo:[0,1] neg_hi:[0,1]
	v_pk_mul_f32 v[220:221], v[220:221], v[170:171] op_sel_hi:[1,0]
	v_pk_mul_f32 v[222:223], v[222:223], v[170:171] op_sel_hi:[1,0]
	v_pk_fma_f32 v[220:221], v[108:109], v[220:221], v[146:147]
	v_pk_fma_f32 v[222:223], v[110:111], v[222:223], v[148:149]
	v_pk_fma_f32 v[0:1], v[220:221], s[8:9], v[0:1] op_sel_hi:[1,0,1]
	v_pk_fma_f32 v[2:3], v[222:223], s[8:9], v[2:3] op_sel_hi:[1,0,1]
	global_store_dwordx4 v[230:231], v[0:3], off offset:192
	v_readlane_b32 s9, v242, 26
	v_readlane_b32 s10, v242, 27
	v_readlane_b32 s11, v242, 28
	v_readlane_b32 s12, v242, 29
	v_readlane_b32 s13, v242, 30
	v_readlane_b32 s14, v242, 31
	v_readlane_b32 s15, v242, 32
	v_readlane_b32 s16, v242, 33
	v_readlane_b32 s17, v242, 34
	v_readlane_b32 s18, v242, 35
	v_readlane_b32 s19, v242, 36
	v_readlane_b32 s20, v242, 37
	v_readlane_b32 s21, v242, 38
	v_readlane_b32 s22, v242, 39
	v_readlane_b32 s23, v242, 40
	s_mov_b64 s[24:25], 0x5000
	s_movk_i32 s6, 0xfff
	s_waitcnt lgkmcnt(0)
	s_barrier
	s_cmpk_gt_i32 s5, 0xff
	s_cbranch_scc0 .LBB0_52

.LBB0_119:
	v_readlane_b32 s5, v241, 20
	v_readlane_b32 s6, v238, 23
	v_readlane_b32 s8, v243, 5
	v_add_u32_e32 v60, s5, v68
	v_add_u32_e32 v32, 0xfffff000, v60
	v_lshrrev_b32_e32 v32, 10, v32
	s_movk_i32 s5, 0xfff
	v_add_u32_e32 v32, 1, v32
	v_cmp_lt_i32_e32 vcc, s5, v60
	s_mul_i32 s5, s6, 3
	v_readlane_b32 s14, v243, 11
	v_cndmask_b32_e32 v32, 0, v32, vcc
	v_readlane_b32 s15, v243, 12
	v_readlane_b32 s7, v238, 24
	v_add_u32_e32 v34, s5, v32
	v_mov_b64_e32 v[32:33], s[14:15]
	v_mad_i64_i32 v[32:33], s[6:7], v34, s33, v[32:33]
	s_mov_b64 s[6:7], 0x3000
	s_nop 0
	v_lshl_add_u64 v[52:53], v[32:33], 0, s[6:7]
	s_mov_b64 s[6:7], 0x4000
	v_lshl_add_u64 v[54:55], v[32:33], 0, s[6:7]
	v_mov_b32_e32 v41, v129
	v_mov_b32_e32 v43, v129
	v_mov_b32_e32 v45, v129
	v_lshl_add_u64 v[66:67], v[52:53], 0, v[128:129]
	v_lshl_add_u64 v[64:65], v[54:55], 0, v[128:129]
	v_lshl_add_u64 v[62:63], v[52:53], 0, v[40:41]
	v_lshl_add_u64 v[58:59], v[54:55], 0, v[40:41]
	v_lshl_add_u64 v[56:57], v[52:53], 0, v[42:43]
	v_lshl_add_u64 v[34:35], v[54:55], 0, v[42:43]
	v_lshl_add_u64 v[32:33], v[52:53], 0, v[44:45]
	v_lshl_add_u64 v[52:53], v[54:55], 0, v[44:45]
	v_mov_b32_e32 v54, v16
	v_mov_b32_e32 v55, v20
	v_mov_b32_e32 v72, v17
	v_mov_b32_e32 v73, v21
	v_pk_add_f32 v[54:55], v[54:55], v[72:73]
	v_mov_b32_e32 v72, v18
	v_mov_b32_e32 v73, v22
	v_pk_add_f32 v[54:55], v[72:73], v[54:55]
	v_mov_b32_e32 v72, v19
	v_mov_b32_e32 v73, v23
	v_pk_add_f32 v[54:55], v[72:73], v[54:55]
	v_mov_b32_e32 v72, v25
	v_add_f32_e32 v41, 0, v54
	v_add_f32_e32 v41, v41, v55
	v_mov_b32_e32 v54, v24
	v_mov_b32_e32 v55, v28
	v_mov_b32_e32 v73, v29
	v_pk_add_f32 v[54:55], v[54:55], v[72:73]
	v_mov_b32_e32 v72, v26
	v_mov_b32_e32 v73, v30
	v_pk_add_f32 v[54:55], v[72:73], v[54:55]
	v_mov_b32_e32 v72, v27
	v_mov_b32_e32 v73, v31
	v_pk_add_f32 v[54:55], v[72:73], v[54:55]
	global_load_dwordx4 v[72:75], v[48:49], off offset:3072
	global_load_dwordx4 v[76:79], v[46:47], off offset:3072
	v_add_f32_e32 v41, v41, v54
	v_add_f32_e32 v41, v41, v55
	global_load_dwordx4 v[80:83], v[48:49], off offset:2048
	global_load_dwordx4 v[84:87], v[46:47], off offset:2048
	v_add_f32_dpp v41, v41, v41 quad_perm:[1,0,3,2] row_mask:0xf bank_mask:0xf bound_ctrl:1
	s_mov_b32 s5, 0x800000
	v_ashrrev_i32_e32 v61, 31, v60
	v_add_f32_dpp v41, v41, v41 quad_perm:[2,3,0,1] row_mask:0xf bank_mask:0xf bound_ctrl:1
	v_readlane_b32 s9, v243, 6
	v_readlane_b32 s10, v243, 7
	v_add_f32_dpp v41, v41, v41 row_half_mirror row_mask:0xf bank_mask:0xf bound_ctrl:1
	v_readlane_b32 s11, v243, 8
	v_readlane_b32 s12, v243, 9
	v_add_f32_dpp v41, v41, v41 row_mirror row_mask:0xf bank_mask:0xf bound_ctrl:1
	ds_bpermute_b32 v43, v69, v41
	v_readlane_b32 s13, v243, 10
	v_readlane_b32 s16, v243, 13
	v_readlane_b32 s17, v243, 14
	v_readlane_b32 s18, v243, 15
	s_waitcnt lgkmcnt(0)
	v_add_f32_e32 v41, v41, v43
	ds_bpermute_b32 v43, v70, v41
	v_readlane_b32 s19, v243, 16
	v_readlane_b32 s20, v243, 17
	v_readlane_b32 s21, v243, 18
	v_readlane_b32 s22, v243, 19
	s_waitcnt lgkmcnt(0)
	v_add_f32_e32 v41, v41, v43
	v_mul_f32_e32 v54, 0x3a800000, v41
	v_mov_b32_e32 v112, v54
	v_pk_add_f32 v[92:93], v[28:29], v[54:55] op_sel_hi:[1,0] neg_lo:[0,1] neg_hi:[0,1]
	v_pk_add_f32 v[96:97], v[24:25], v[54:55] op_sel_hi:[1,0] neg_lo:[0,1] neg_hi:[0,1]
	v_pk_add_f32 v[98:99], v[26:27], v[54:55] op_sel_hi:[1,0] neg_lo:[0,1] neg_hi:[0,1]
	v_mov_b32_e32 v26, v93
	v_mov_b32_e32 v27, v97
	v_pk_add_f32 v[94:95], v[30:31], v[54:55] op_sel_hi:[1,0] neg_lo:[0,1] neg_hi:[0,1]
	v_mov_b32_e32 v24, v92
	v_mov_b32_e32 v25, v96
	v_pk_mul_f32 v[26:27], v[26:27], v[26:27]
	v_mov_b32_e32 v28, v95
	v_pk_fma_f32 v[24:25], v[24:25], v[24:25], v[26:27]
	v_mov_b32_e32 v26, v94
	v_mov_b32_e32 v27, v98
	v_mov_b32_e32 v29, v99
	v_pk_fma_f32 v[24:25], v[26:27], v[26:27], v[24:25]
	v_pk_add_f32 v[102:103], v[20:21], v[54:55] op_sel_hi:[1,0] neg_lo:[0,1] neg_hi:[0,1]
	v_pk_fma_f32 v[100:101], v[28:29], v[28:29], v[24:25]
	global_load_dwordx4 v[24:27], v[48:49], off offset:1024
	global_load_dwordx4 v[88:91], v[46:47], off offset:1024
	v_pk_add_f32 v[104:105], v[22:23], v[54:55] op_sel_hi:[1,0] neg_lo:[0,1] neg_hi:[0,1]
	global_load_dwordx4 v[20:23], v[48:49], off
	global_load_dwordx4 v[28:31], v[46:47], off
	v_pk_add_f32 v[16:17], v[16:17], v[54:55] op_sel_hi:[1,0] neg_lo:[0,1] neg_hi:[0,1]
	v_mov_b32_e32 v107, v103
	v_mov_b32_e32 v106, v17
	v_pk_add_f32 v[18:19], v[18:19], v[54:55] op_sel_hi:[1,0] neg_lo:[0,1] neg_hi:[0,1]
	v_mov_b32_e32 v54, v16
	v_mov_b32_e32 v55, v102
	v_pk_mul_f32 v[106:107], v[106:107], v[106:107]
	v_mov_b32_e32 v108, v19
	v_pk_fma_f32 v[54:55], v[54:55], v[54:55], v[106:107]
	v_mov_b32_e32 v106, v18
	v_mov_b32_e32 v107, v104
	v_mov_b32_e32 v109, v105
	v_pk_fma_f32 v[54:55], v[106:107], v[106:107], v[54:55]
	v_readlane_b32 s23, v243, 20
	v_pk_fma_f32 v[54:55], v[108:109], v[108:109], v[54:55]
	s_nop 0
	v_add_f32_e32 v41, v54, v55
	v_add_f32_e32 v41, v101, v41
	v_add_f32_e32 v41, v100, v41
	s_nop 1
	v_add_f32_dpp v41, v41, v41 quad_perm:[1,0,3,2] row_mask:0xf bank_mask:0xf bound_ctrl:1
	s_nop 1
	v_add_f32_dpp v41, v41, v41 quad_perm:[2,3,0,1] row_mask:0xf bank_mask:0xf bound_ctrl:1
	s_nop 1
	v_add_f32_dpp v41, v41, v41 row_half_mirror row_mask:0xf bank_mask:0xf bound_ctrl:1
	s_nop 1
	v_add_f32_dpp v41, v41, v41 row_mirror row_mask:0xf bank_mask:0xf bound_ctrl:1
	ds_bpermute_b32 v43, v69, v41
	s_waitcnt lgkmcnt(0)
	v_add_f32_e32 v41, v41, v43
	ds_bpermute_b32 v43, v70, v41
	s_waitcnt lgkmcnt(0)
	v_add_f32_e32 v41, v41, v43
	v_fmamk_f32 v41, v41, 0x3a800000, v177
	v_cmp_gt_f32_e32 vcc, s5, v41
	v_mul_f32_e32 v43, 0x4b800000, v41
	v_readlane_b32 s5, v240, 54
	v_cndmask_b32_e32 v41, v41, v43, vcc
	v_rsq_f32_e32 v41, v41
	v_add_u32_e32 v68, s5, v68
	v_mul_f32_e32 v43, 0x45800000, v41
	v_cndmask_b32_e32 v54, v41, v43, vcc
	v_mov_b32_e32 v113, v54
	v_pk_mul_f32 v[16:17], v[16:17], v[54:55] op_sel_hi:[1,0]
	s_and_b64 vcc, exec, s[0:1]
	s_waitcnt vmcnt(0)
	v_pk_fma_f32 v[28:29], v[20:21], v[16:17], v[28:29]
	v_pk_mul_f32 v[16:17], v[18:19], v[54:55] op_sel_hi:[1,0]
	v_pk_mul_f32 v[18:19], v[94:95], v[54:55] op_sel_hi:[1,0]
	v_pk_fma_f32 v[30:31], v[22:23], v[16:17], v[30:31]
	v_pk_mul_f32 v[16:17], v[102:103], v[54:55] op_sel_hi:[1,0]
	v_pk_fma_f32 v[18:19], v[74:75], v[18:19], v[78:79]
	v_pk_fma_f32 v[24:25], v[24:25], v[16:17], v[88:89]
	v_pk_mul_f32 v[16:17], v[104:105], v[54:55] op_sel_hi:[1,0]
	s_nop 0
	v_pk_fma_f32 v[26:27], v[26:27], v[16:17], v[90:91]
	v_pk_mul_f32 v[16:17], v[96:97], v[54:55] op_sel_hi:[1,0]
	s_nop 0
	v_pk_fma_f32 v[20:21], v[80:81], v[16:17], v[84:85]
	v_pk_mul_f32 v[16:17], v[98:99], v[54:55] op_sel_hi:[1,0]
	s_nop 0
	v_pk_fma_f32 v[22:23], v[82:83], v[16:17], v[86:87]
	v_pk_mul_f32 v[16:17], v[92:93], v[54:55] op_sel_hi:[1,0]
	v_lshlrev_b64 v[114:115], 3, v[60:61]
	v_lshlrev_b64 v[54:55], 12, v[60:61]
	v_lshl_add_u64 v[114:115], v[38:39], 0, v[114:115]
	v_pk_fma_f32 v[16:17], v[72:73], v[16:17], v[76:77]
	global_load_dwordx4 v[72:75], v[66:67], off
	s_nop 0
	global_load_dwordx4 v[64:67], v[64:65], off
	v_lshl_add_u64 v[54:55], v[38:39], 0, v[54:55]
	v_lshlrev_b64 v[60:61], 11, v[60:61]
	v_lshl_add_u64 v[60:61], v[50:51], 0, v[60:61]
	s_waitcnt vmcnt(0)
	v_pk_add_f32 v[64:65], v[64:65], 1.0 op_sel_hi:[1,0]
	v_pk_add_f32 v[66:67], v[66:67], 1.0 op_sel_hi:[1,0]
	v_pk_fma_f32 v[64:65], v[64:65], v[28:29], v[72:73]
	v_pk_fma_f32 v[66:67], v[66:67], v[30:31], v[74:75]
	global_load_dwordx4 v[72:75], v[62:63], off
	global_load_dwordx4 v[76:79], v[58:59], off
	v_cvt_pk_bf16_f32 v64, v64, v65
	v_cvt_pk_bf16_f32 v65, v66, v67
	s_waitcnt vmcnt(0)
	v_pk_add_f32 v[58:59], v[76:77], 1.0 op_sel_hi:[1,0]
	v_pk_add_f32 v[62:63], v[78:79], 1.0 op_sel_hi:[1,0]
	v_pk_fma_f32 v[58:59], v[58:59], v[24:25], v[72:73]
	v_pk_fma_f32 v[62:63], v[62:63], v[26:27], v[74:75]
	global_load_dwordx4 v[72:75], v[56:57], off
	global_load_dwordx4 v[76:79], v[34:35], off
	v_cvt_pk_bf16_f32 v58, v58, v59
	v_cvt_pk_bf16_f32 v59, v62, v63
	s_waitcnt vmcnt(0)
	v_pk_add_f32 v[34:35], v[76:77], 1.0 op_sel_hi:[1,0]
	s_nop 0
	v_pk_fma_f32 v[34:35], v[34:35], v[20:21], v[72:73]
	s_nop 0
	v_cvt_pk_bf16_f32 v56, v34, v35
	v_pk_add_f32 v[34:35], v[78:79], 1.0 op_sel_hi:[1,0]
	s_nop 0
	v_pk_fma_f32 v[34:35], v[34:35], v[22:23], v[74:75]
	s_nop 0
	v_cvt_pk_bf16_f32 v57, v34, v35
	global_load_dwordx4 v[32:35], v[32:33], off
	s_nop 0
	global_load_dwordx4 v[72:75], v[52:53], off
	s_nop 0
	s_mov_b64 s[98:99], exec
	s_mov_b64 exec, 1
	global_store_dwordx2 v[114:115], v[112:113], off
	s_mov_b64 exec, s[98:99]
	global_store_dwordx2 v[60:61], v[64:65], off
	global_store_dwordx2 v[60:61], v[58:59], off offset:512
	global_store_dwordx2 v[60:61], v[56:57], off offset:1024
	v_mov_b64_e32 v[22:23], v[10:11]
	v_mov_b64_e32 v[26:27], v[6:7]
	v_mov_b64_e32 v[30:31], v[2:3]
	v_mov_b64_e32 v[20:21], v[8:9]
	v_mov_b64_e32 v[24:25], v[4:5]
	v_mov_b64_e32 v[28:29], v[0:1]
	s_waitcnt vmcnt(4)
	v_pk_add_f32 v[52:53], v[72:73], 1.0 op_sel_hi:[1,0]
	s_nop 0
	v_pk_fma_f32 v[32:33], v[52:53], v[16:17], v[32:33]
	v_pk_add_f32 v[16:17], v[74:75], 1.0 op_sel_hi:[1,0]
	v_cvt_pk_bf16_f32 v32, v32, v33
	v_pk_fma_f32 v[16:17], v[16:17], v[18:19], v[34:35]
	s_nop 0
	v_cvt_pk_bf16_f32 v33, v16, v17
	v_mov_b64_e32 v[18:19], v[14:15]
	v_mov_b64_e32 v[16:17], v[12:13]
	global_store_dwordx2 v[60:61], v[32:33], off offset:1536
	s_cbranch_vccnz .LBB0_122
